# NA bias/mask apply: 32 exec-masked table reads batched into free VGPRs + v_cndmask (no per-element LDS wait)
# speedup vs baseline: 1.0041x; 1.0041x over previous
; template <bool DIFF>
; __device__ __forceinline__ void qkt(f32x16& a, f32x16& b, const char* Ks, const char* Qs, int krow, int r32, int hi) {
;   a = f32x16{}; b = f32x16{};
; #pragma unroll
;   for (int d = 0; d < 4; ++d) {
;     const int cb0 = (d * 16 + hi * 8) * 2, cb1 = ((d + 4) * 16 + hi * 8) * 2;
;     const bf16x8 k0 = *reinterpret_cast<const bf16x8*>(Ks + KSWZ(krow, cb0)), q0 = *reinterpret_cast<const bf16x8*>(Qs + KSWZ(r32, cb0));
;     const bf16x8 k1 = *reinterpret_cast<const bf16x8*>(Ks + KSWZ(krow, cb1)), q1 = *reinterpret_cast<const bf16x8*>(Qs + KSWZ(r32, cb1));
;     a = __builtin_amdgcn_mfma_f32_32x32x16_bf16(k0, q0, a, 0, 0, 0);
;     b = __builtin_amdgcn_mfma_f32_32x32x16_bf16(k1, q1, b, 0, 0, 0); }
;   if (!DIFF) {
; #pragma unroll
;     for (int r = 0; r < 16; ++r) a[r] += b[r]; }
; }
.LBB0_369:
	v_cmp_ge_u32_e32 vcc, s40, v159
	v_cmp_lt_u32_e64 s[40:41], s40, v160
	s_and_b64 s[88:89], vcc, s[40:41]
	s_and_saveexec_b64 s[40:41], s[88:89]
	s_cbranch_execz .LBB0_439
	v_add_u32_e32 v78, v161, v162
	ds_read_b128 v[66:69], v78
	ds_read_b128 v[70:73], v175 offset:36864
	v_add_u32_e32 v79, v161, v163
	ds_read_b128 v[74:77], v79
	ds_read_b128 v[82:85], v176 offset:36864
	v_add_u32_e32 v153, v161, v164
	v_add_u32_e32 v185, v161, v165
	s_waitcnt lgkmcnt(2)
	v_mfma_f32_32x32x16_bf16 v[98:113], v[66:69], v[70:73], 0
	ds_read_b128 v[66:69], v153
	ds_read_b128 v[186:189], v177 offset:36864
	v_add_u32_e32 v206, v161, v166
	v_add_u32_e32 v207, v161, v167
	v_add_u32_e32 v209, v161, v168
	v_add_u32_e32 v222, v161, v169
	s_waitcnt lgkmcnt(2)
	v_mfma_f32_32x32x16_bf16 v[114:129], v[74:77], v[82:85], 0
	ds_read_b128 v[74:77], v185
	ds_read_b128 v[190:193], v178 offset:36864
	s_waitcnt lgkmcnt(2)
	v_mfma_f32_32x32x16_bf16 v[98:113], v[66:69], v[186:189], v[98:113]
	ds_read_b128 v[66:69], v206
	ds_read_b128 v[194:197], v179 offset:36864
	s_waitcnt lgkmcnt(2)
	v_mfma_f32_32x32x16_bf16 v[114:129], v[74:77], v[190:193], v[114:129]
	ds_read_b128 v[74:77], v207
	ds_read_b128 v[198:201], v180 offset:36864
	s_waitcnt lgkmcnt(2)
	v_mfma_f32_32x32x16_bf16 v[98:113], v[66:69], v[194:197], v[98:113]
	ds_read_b128 v[66:69], v209
	ds_read_b128 v[202:205], v181 offset:36864
	s_waitcnt lgkmcnt(2)
	v_mfma_f32_32x32x16_bf16 v[114:129], v[74:77], v[198:201], v[114:129]
	ds_read_b128 v[74:77], v222
	ds_read_b128 v[210:213], v182 offset:36864
	s_waitcnt lgkmcnt(2)
	v_mfma_f32_32x32x16_bf16 v[98:113], v[66:69], v[202:205], v[98:113]
	ds_read_b128 v[66:69], v78 offset:8192
	ds_read_b128 v[86:89], v79 offset:8192
	ds_read_b128 v[214:217], v153 offset:8192
	ds_read_b128 v[218:221], v185 offset:8192
	s_waitcnt lgkmcnt(4)
	v_mfma_f32_32x32x16_bf16 v[114:129], v[74:77], v[210:213], v[114:129]
	s_waitcnt lgkmcnt(3)
	v_mfma_f32_32x32x16_bf16 v[66:81], v[66:69], v[70:73], 0
	s_waitcnt lgkmcnt(2)
	v_mfma_f32_32x32x16_bf16 v[82:97], v[86:89], v[82:85], 0
	s_waitcnt lgkmcnt(1)
	v_mfma_f32_32x32x16_bf16 v[66:81], v[214:217], v[186:189], v[66:81]
	s_waitcnt lgkmcnt(0)
	v_mfma_f32_32x32x16_bf16 v[82:97], v[218:221], v[190:193], v[82:97]
	ds_read_b128 v[186:189], v206 offset:8192
	ds_read_b128 v[190:193], v207 offset:8192
	s_waitcnt lgkmcnt(1)
	v_mfma_f32_32x32x16_bf16 v[66:81], v[186:189], v[194:197], v[66:81]
	s_waitcnt lgkmcnt(0)
	v_mfma_f32_32x32x16_bf16 v[82:97], v[190:193], v[198:201], v[82:97]
	ds_read_b128 v[186:189], v209 offset:8192
	ds_read_b128 v[190:193], v222 offset:8192
	s_waitcnt lgkmcnt(1)
	v_mfma_f32_32x32x16_bf16 v[66:81], v[186:189], v[202:205], v[66:81]
	s_waitcnt lgkmcnt(0)
	v_mfma_f32_32x32x16_bf16 v[82:97], v[190:193], v[210:213], v[82:97]
	ds_read_b32 v223, v170
	ds_read_b32 v224, v170 offset:4
	ds_read_b32 v225, v170 offset:8
	ds_read_b32 v226, v170 offset:12
	ds_read_b32 v227, v170 offset:32
	ds_read_b32 v228, v170 offset:36
	ds_read_b32 v229, v170 offset:40
	ds_read_b32 v230, v170 offset:44
	ds_read_b32 v231, v170 offset:64
	ds_read_b32 v232, v170 offset:68
	ds_read_b32 v233, v170 offset:72
	ds_read_b32 v234, v170 offset:76
	ds_read_b32 v235, v170 offset:96
	ds_read_b32 v236, v170 offset:100
	ds_read_b32 v237, v170 offset:104
	ds_read_b32 v238, v170 offset:108
	ds_read_b32 v239, v170 offset:128
	ds_read_b32 v240, v170 offset:132
	ds_read_b32 v241, v170 offset:136
	ds_read_b32 v242, v170 offset:140
	ds_read_b32 v243, v170 offset:160
	ds_read_b32 v244, v170 offset:164
	ds_read_b32 v245, v170 offset:168
	ds_read_b32 v246, v170 offset:172
	ds_read_b32 v247, v170 offset:192
	ds_read_b32 v248, v170 offset:196
	ds_read_b32 v249, v170 offset:200
	ds_read_b32 v250, v170 offset:204
	ds_read_b32 v251, v170 offset:224
	ds_read_b32 v252, v170 offset:228
	ds_read_b32 v253, v170 offset:232
	ds_read_b32 v254, v170 offset:236
	v_mov_b32_e32 v153, 0xf149f2ca
	v_mov_b32_e32 v185, 0xf149f2ca
	v_add_f32_e32 v98, v98, v114
	s_waitcnt lgkmcnt(15)
	v_add_f32_e32 v98, v98, v223
	v_cndmask_b32_e64 v185, v185, v98, s[4:5]
	v_add_f32_e32 v98, v99, v115
	s_waitcnt lgkmcnt(15)
	v_add_f32_e32 v98, v98, v224
	v_cndmask_b32_e64 v153, v153, v98, s[6:7]
	v_mov_b32_e32 v98, 0xf149f2ca
	v_mov_b32_e32 v99, 0xf149f2ca
	v_add_f32_e32 v100, v100, v116
	s_waitcnt lgkmcnt(15)
	v_add_f32_e32 v100, v100, v225
	v_cndmask_b32_e64 v99, v99, v100, s[8:9]
	v_add_f32_e32 v100, v101, v117
	s_waitcnt lgkmcnt(15)
	v_add_f32_e32 v100, v100, v226
	v_cndmask_b32_e64 v98, v98, v100, s[10:11]
	v_mov_b32_e32 v100, 0xf149f2ca
	v_mov_b32_e32 v101, 0xf149f2ca
	v_add_f32_e32 v102, v102, v118
	s_waitcnt lgkmcnt(15)
	v_add_f32_e32 v102, v102, v227
	v_cndmask_b32_e64 v101, v101, v102, s[12:13]
	v_add_f32_e32 v102, v103, v119
	s_waitcnt lgkmcnt(15)
	v_add_f32_e32 v102, v102, v228
	v_cndmask_b32_e64 v100, v100, v102, s[14:15]
	v_mov_b32_e32 v102, 0xf149f2ca
	v_mov_b32_e32 v103, 0xf149f2ca
	v_add_f32_e32 v104, v104, v120
	s_waitcnt lgkmcnt(15)
	v_add_f32_e32 v104, v104, v229
	v_cndmask_b32_e64 v103, v103, v104, s[16:17]
	v_add_f32_e32 v104, v105, v121
	s_waitcnt lgkmcnt(15)
	v_add_f32_e32 v104, v104, v230
	v_cndmask_b32_e64 v102, v102, v104, s[18:19]
	v_mov_b32_e32 v104, 0xf149f2ca
	v_mov_b32_e32 v105, 0xf149f2ca
	v_add_f32_e32 v106, v106, v122
	s_waitcnt lgkmcnt(15)
	v_add_f32_e32 v106, v106, v231
	v_cndmask_b32_e64 v105, v105, v106, s[54:55]
	v_add_f32_e32 v106, v107, v123
	s_waitcnt lgkmcnt(15)
	v_add_f32_e32 v106, v106, v232
	v_cndmask_b32_e64 v104, v104, v106, s[56:57]
	v_mov_b32_e32 v106, 0xf149f2ca
	v_mov_b32_e32 v107, 0xf149f2ca
	v_add_f32_e32 v108, v108, v124
	s_waitcnt lgkmcnt(15)
; __device__ __forceinline__ int crow(int r, int hi) { return (r & 3) + 8 * (r >> 2) + 4 * hi; }
; template <bool DIFF> ...
;     ...
;         BIAS_APPLY(t, 0, a0, b0, cb0); BIAS_APPLY(t, 1, a1, b1, cb1);
;         float mx = a0[0];
; #pragma unroll
;         for (int r = 1; r < 16; ++r) mx = fmaxf(mx, a0[r]);
; #pragma unroll
;         for (int r = 0; r < 16; ++r) mx = fmaxf(mx, a1[r]);
;         { auto rr = __builtin_amdgcn_permlane32_swap(__float_as_uint(mx), __float_as_uint(mx), false, false); mx = fmaxf(__uint_as_float(rr[0]), __uint_as_float(rr[1])); }
;         const float mn = fmaxf(m1, mx), alpha = __builtin_amdgcn_exp2f((m1 - mn) * C), x1 = -mn * C; m1 = mn;
;         float ps = 0.f;
; #pragma unroll
;         for (int r = 0; r < 16; ++r) { a0[r] = __builtin_amdgcn_exp2f(fmaf(a0[r], C, x1)); ps += a0[r]; }
; #pragma unroll
;         for (int r = 0; r < 16; ++r) { a1[r] = __builtin_amdgcn_exp2f(fmaf(a1[r], C, x1)); ps += a1[r]; }
;         l1 = l1 * alpha + ps;
;         if (__any(alpha < 1.0f)) {
;           if (hi == 0) wsc[r32] = alpha;
;           asm volatile("s_waitcnt lgkmcnt(0)" ::: "memory");
; #pragma unroll
;           for (int r = 0; r < 16; ++r) { const float al = wsc[crow(r, hi)];
; #pragma unroll
;             for (int d = 0; d < 4; ++d) o[d][r] *= al; }
;         }
	v_add_f32_e32 v108, v108, v233
	v_cndmask_b32_e64 v107, v107, v108, s[58:59]
	v_add_f32_e32 v108, v109, v125
	s_waitcnt lgkmcnt(15)
	v_add_f32_e32 v108, v108, v234
	v_cndmask_b32_e64 v106, v106, v108, s[60:61]
	v_mov_b32_e32 v108, 0xf149f2ca
	v_mov_b32_e32 v109, 0xf149f2ca
	v_add_f32_e32 v110, v110, v126
	s_waitcnt lgkmcnt(15)
	v_add_f32_e32 v110, v110, v235
	v_cndmask_b32_e64 v109, v109, v110, s[62:63]
	v_add_f32_e32 v110, v111, v127
	s_waitcnt lgkmcnt(15)
	v_add_f32_e32 v110, v110, v236
	v_cndmask_b32_e64 v108, v108, v110, s[64:65]
	v_mov_b32_e32 v110, 0xf149f2ca
	v_mov_b32_e32 v111, 0xf149f2ca
	v_add_f32_e32 v112, v112, v128
	s_waitcnt lgkmcnt(15)
	v_add_f32_e32 v112, v112, v237
	v_cndmask_b32_e64 v111, v111, v112, s[66:67]
	v_add_f32_e32 v112, v113, v129
	s_waitcnt lgkmcnt(15)
	v_add_f32_e32 v112, v112, v238
	v_cndmask_b32_e64 v110, v110, v112, s[68:69]
	v_mov_b32_e32 v112, 0xf149f2ca
	v_mov_b32_e32 v113, 0xf149f2ca
	v_add_f32_e32 v66, v66, v82
	s_waitcnt lgkmcnt(15)
	v_add_f32_e32 v66, v66, v239
	v_cndmask_b32_e64 v113, v113, v66, s[70:71]
	v_add_f32_e32 v66, v67, v83
	s_waitcnt lgkmcnt(14)
	v_add_f32_e32 v66, v66, v240
	v_cndmask_b32_e64 v112, v112, v66, s[72:73]
	v_mov_b32_e32 v66, 0xf149f2ca
	v_mov_b32_e32 v67, 0xf149f2ca
	v_add_f32_e32 v68, v68, v84
	s_waitcnt lgkmcnt(13)
	v_add_f32_e32 v68, v68, v241
	v_cndmask_b32_e64 v67, v67, v68, s[74:75]
	v_add_f32_e32 v68, v69, v85
	s_waitcnt lgkmcnt(12)
	v_add_f32_e32 v68, v68, v242
	v_cndmask_b32_e64 v66, v66, v68, s[76:77]
	v_mov_b32_e32 v69, 0xf149f2ca
	v_mov_b32_e32 v82, 0xf149f2ca
	v_add_f32_e32 v68, v70, v86
	s_waitcnt lgkmcnt(11)
	v_add_f32_e32 v68, v68, v243
	v_cndmask_b32_e64 v82, v82, v68, s[78:79]
	v_add_f32_e32 v68, v71, v87
	s_waitcnt lgkmcnt(10)
	v_add_f32_e32 v68, v68, v244
	v_cndmask_b32_e64 v69, v69, v68, s[80:81]
	v_mov_b32_e32 v70, 0xf149f2ca
	v_mov_b32_e32 v71, 0xf149f2ca
	v_add_f32_e32 v68, v72, v88
	s_waitcnt lgkmcnt(9)
	v_add_f32_e32 v68, v68, v245
	v_cndmask_b32_e64 v71, v71, v68, s[82:83]
	v_add_f32_e32 v68, v73, v89
	s_waitcnt lgkmcnt(8)
	v_add_f32_e32 v68, v68, v246
	v_cndmask_b32_e64 v70, v70, v68, s[84:85]
	v_mov_b32_e32 v72, 0xf149f2ca
	v_mov_b32_e32 v73, 0xf149f2ca
	v_add_f32_e32 v68, v74, v90
	s_waitcnt lgkmcnt(7)
	v_add_f32_e32 v68, v68, v247
	v_cndmask_b32_e64 v73, v73, v68, s[20:21]
	v_add_f32_e32 v68, v75, v91
	s_waitcnt lgkmcnt(6)
	v_add_f32_e32 v68, v68, v248
	v_cndmask_b32_e64 v72, v72, v68, s[22:23]
	v_mov_b32_e32 v74, 0xf149f2ca
	v_mov_b32_e32 v75, 0xf149f2ca
	v_add_f32_e32 v68, v76, v92
	s_waitcnt lgkmcnt(5)
	v_add_f32_e32 v68, v68, v249
	v_cndmask_b32_e64 v75, v75, v68, s[24:25]
	v_add_f32_e32 v68, v77, v93
	s_waitcnt lgkmcnt(4)
	v_add_f32_e32 v68, v68, v250
	v_cndmask_b32_e64 v74, v74, v68, s[26:27]
	v_mov_b32_e32 v76, 0xf149f2ca
	v_mov_b32_e32 v77, 0xf149f2ca
	v_add_f32_e32 v68, v78, v94
	s_waitcnt lgkmcnt(3)
	v_add_f32_e32 v68, v68, v251
	v_cndmask_b32_e64 v77, v77, v68, s[28:29]
	v_add_f32_e32 v68, v79, v95
	s_waitcnt lgkmcnt(2)
	v_add_f32_e32 v68, v68, v252
	v_cndmask_b32_e64 v76, v76, v68, s[30:31]
	v_mov_b32_e32 v78, 0xf149f2ca
	v_mov_b32_e32 v79, 0xf149f2ca
	v_add_f32_e32 v68, v80, v96
	s_waitcnt lgkmcnt(1)
	v_add_f32_e32 v68, v68, v253
	v_cndmask_b32_e64 v79, v79, v68, s[34:35]
	v_add_f32_e32 v68, v81, v97
	s_waitcnt lgkmcnt(0)
	v_add_f32_e32 v68, v68, v254
	v_cndmask_b32_e64 v78, v78, v68, s[36:37]
	v_max_f32_e32 v68, v153, v153
	v_max_f32_e32 v80, v185, v185
	v_max_f32_e32 v68, v80, v68
	v_max3_f32 v68, v68, v99, v98
	v_max3_f32 v68, v68, v101, v100
	v_max3_f32 v68, v68, v103, v102
	v_max3_f32 v68, v68, v105, v104
	v_max3_f32 v68, v68, v107, v106
	v_max3_f32 v68, v68, v109, v108
	v_max3_f32 v68, v68, v111, v110
	v_max3_f32 v68, v68, v113, v112
	v_max3_f32 v68, v68, v67, v66
	v_max3_f32 v68, v68, v82, v69
	v_max3_f32 v68, v68, v71, v70
	v_max3_f32 v68, v68, v73, v72
	v_max3_f32 v68, v68, v75, v74
	v_max3_f32 v68, v68, v77, v76
	v_max3_f32 v68, v68, v79, v78
	v_mov_b32_e32 v80, v68
	s_nop 1
	v_permlane32_swap_b32_e32 v68, v80
	v_max3_f32 v68, v184, v68, v80
	v_sub_f32_e32 v80, v184, v68
	v_mul_f32_e32 v80, 0x3e0293ee, v80
	v_exp_f32_e32 v80, v80
	s_nop 0
	v_cmp_gt_f32_e32 vcc, 1.0, v80
	s_cbranch_vccz .LBB0_438
	s_and_saveexec_b64 s[88:89], s[38:39]
	ds_write_b32 v157, v80 offset:34816
	s_or_b64 exec, exec, s[88:89]
	s_waitcnt lgkmcnt(0)
	v_add_u32_e32 v81, v156, v0
	ds_read_b128 v[84:87], v81 offset:34912
	ds_read_b128 v[88:91], v81 offset:34880
	ds_read_b128 v[92:95], v81 offset:34848
	ds_read_b128 v[114:117], v81 offset:34816
	s_waitcnt lgkmcnt(3)
	v_pk_mul_f32 v[62:63], v[62:63], v[84:85]
	s_waitcnt lgkmcnt(2)
	v_pk_mul_f32 v[58:59], v[58:59], v[88:89]
	s_waitcnt lgkmcnt(1)
	v_pk_mul_f32 v[54:55], v[54:55], v[92:93]
	v_pk_mul_f32 v[64:65], v[64:65], v[86:87]
	v_pk_mul_f32 v[60:61], v[60:61], v[90:91]
	v_pk_mul_f32 v[56:57], v[56:57], v[94:95]
	s_waitcnt lgkmcnt(0)
	v_pk_mul_f32 v[52:53], v[52:53], v[116:117]
	v_pk_mul_f32 v[50:51], v[50:51], v[114:115]
	v_pk_mul_f32 v[46:47], v[46:47], v[84:85]
	v_pk_mul_f32 v[42:43], v[42:43], v[88:89]
	v_pk_mul_f32 v[38:39], v[38:39], v[92:93]
	v_pk_mul_f32 v[48:49], v[48:49], v[86:87]
	v_pk_mul_f32 v[44:45], v[44:45], v[90:91]
	v_pk_mul_f32 v[40:41], v[40:41], v[94:95]
	v_pk_mul_f32 v[36:37], v[36:37], v[116:117]
	v_pk_mul_f32 v[34:35], v[34:35], v[114:115]
	v_pk_mul_f32 v[30:31], v[30:31], v[84:85]
	v_pk_mul_f32 v[26:27], v[26:27], v[88:89]
	v_pk_mul_f32 v[22:23], v[22:23], v[92:93]
	v_pk_mul_f32 v[32:33], v[32:33], v[86:87]
	v_pk_mul_f32 v[28:29], v[28:29], v[90:91]
	v_pk_mul_f32 v[24:25], v[24:25], v[94:95]
	v_pk_mul_f32 v[20:21], v[20:21], v[116:117]
	v_pk_mul_f32 v[18:19], v[18:19], v[114:115]
	v_pk_mul_f32 v[14:15], v[14:15], v[84:85]
	v_pk_mul_f32 v[10:11], v[10:11], v[88:89]
	v_pk_mul_f32 v[6:7], v[6:7], v[92:93]
	v_pk_mul_f32 v[16:17], v[16:17], v[86:87]
	v_pk_mul_f32 v[12:13], v[12:13], v[90:91]
	v_pk_mul_f32 v[8:9], v[8:9], v[94:95]
	v_pk_mul_f32 v[4:5], v[4:5], v[116:117]
	v_pk_mul_f32 v[2:3], v[2:3], v[114:115]
